# GEMM phase start (in-proj both layers, FFN-up): first 8 tile DMAs issued before waiting on the first unit's row-statistics load (wait becomes vmcnt(8))
# speedup vs baseline: 1.0049x; 1.0010x over previous
; #define PG8_STAGE(bufoff, gbase, voff) do { _Pragma("unroll") for (int _i = 0; _i < 2; ++_i) \
;     __builtin_amdgcn_global_load_lds((const unsigned*)((const char*)(gbase) + (voff)[_i]), (PG8_LAS unsigned*)(lds + (bufoff) + ldsw + _i * 8192), 16, 0, 0); } while (0)
; #define PG8_WAIT_V(n) asm volatile("s_waitcnt vmcnt(" #n ")" ::: "memory")
; #define PG8_BAR __builtin_amdgcn_s_barrier()
; #define PG8_RTAB_LOAD(var, unit) do { if constexpr (Epi::NEEDS_R) { var = *(const uint4*)(E.ssq + (size_t)((unit).pm * BM + (tid >> 1)) * 16 + (tid & 1) * 8); } } while (0)
; #define PG8_RTAB_FIN(var, buf) do { if constexpr (Epi::NEEDS_R) { float ss_ = bflo(var.x) + bfhi(var.x) + bflo(var.y) + bfhi(var.y) + bflo(var.z) + bfhi(var.z) + bflo(var.w) + bfhi(var.w); ss_ += __shfl_xor(ss_, 1); \
;     if (!(tid & 1)) ((PG8_LAS float*)(lds + RT_OFF))[(buf) * 256 + (tid >> 1)] = rsqrtf(ss_ * (1.0f / DM) + EPS); } } while (0)
; template <class Epi>
; DI void gemm_phase(const bf16_t* __restrict__ gA, const bf16_t* __restrict__ gBt, int M, int N, int K, const Epi& E, char* lds_generic) {
;     ...
;   { uint4 rt0_ = {0u, 0u, 0u, 0u}; PG8_RTAB_LOAD(rt0_, cur); PG8_RTAB_FIN(rt0_, 0); }
;   bf16x8 At[4][2], B0[2][2], B1[2][2];
;   const char* cA = (const char*)gA + (size_t)cur.pm * tstep; const char* cB = (const char*)gBt + (size_t)cur.pn * tstep;
;   PG8_STAGE(PG8_SB(0, 0), cB, voffB); PG8_STAGE(PG8_SA(0, 0), cA, voffA); PG8_STAGE(PG8_SB(0, 1), cB + hstep, voffB); PG8_STAGE(PG8_SA(0, 1), cA + hstep, voffA);
;   if (wr == 1) PG8_BAR;
;   PG8_WAIT_V(4); PG8_BAR;
;   PG8_STAGE(PG8_SB(1, 0), cB + kstep, voffB); PG8_STAGE(PG8_SA(1, 0), cA + kstep, voffA); PG8_STAGE(PG8_SB(1, 1), cB + hstep + kstep, voffB);
;   PG8_WAIT_V(6); PG8_BAR;
.LBB0_124:
	s_andn2_b64 vcc, exec, s[84:85]
	s_cbranch_vccnz .LBB0_586
	v_readlane_b32 s4, v255, 52
	v_readlane_b32 s5, v255, 53
	s_mov_b64 s[0:1], -1
	s_and_b64 vcc, exec, s[4:5]
	s_cbranch_vccz .LBB0_147
	v_readlane_b32 s0, v253, 35
	v_mov_b32_e32 v2, v222
	v_readlane_b32 s1, v253, 36
	s_andn2_b64 vcc, exec, s[0:1]
	v_readfirstlane_b32 s4, v2
	s_cbranch_vccnz .LBB0_146
	v_ashrrev_i32_e32 v150, 1, v2
	v_readlane_b32 s0, v254, 49
	v_and_b32_e32 v3, 1, v2
	v_lshlrev_b32_e32 v0, 4, v3
	v_add_u32_e32 v4, s0, v150
	v_ashrrev_i32_e32 v5, 31, v4
	v_lshlrev_b64 v[4:5], 5, v[4:5]
	v_lshl_add_u64 v[4:5], s[70:71], 0, v[4:5]
	v_lshl_add_u64 v[4:5], v[4:5], 0, v[0:1]
	global_load_dwordx4 v[242:245], v[4:5], off
	v_cmp_lt_i32_e32 vcc, v224, v225
	v_cmp_eq_u32_e64 s[36:37], 0, v3
	v_lshl_add_u32 v152, v150, 2, v252
	v_ashrrev_i32_e32 v0, 31, v2
	v_lshrrev_b32_e32 v0, 26, v0
	v_add_u32_e32 v0, v2, v0
	s_waitcnt lgkmcnt(0)
	v_ashrrev_i32_e32 v4, 6, v0
	v_bfe_i32 v0, v2, 27, 1
	v_lshlrev_b32_e32 v7, 4, v2
	v_lshrrev_b32_e32 v0, 22, v0
	v_add_u32_e32 v0, v7, v0
	v_and_b32_e32 v0, 0xfffffc00, v0
	v_sub_u32_e32 v0, v7, v0
	v_lshrrev_b32_e32 v5, 4, v0
	v_bitop3_b32 v0, v5, v0, 32 bitop3:0x6c
	v_lshlrev_b32_e32 v5, 3, v4
	v_and_b32_e32 v6, -16, v5
	v_ashrrev_i32_e32 v5, 31, v0
	v_lshrrev_b32_e32 v5, 26, v5
	v_add_u32_e32 v8, v0, v5
	v_ashrrev_i32_e32 v5, 6, v8
	v_add_u32_e32 v9, v5, v6
	v_lshlrev_b32_e32 v6, 5, v4
	v_and_b32_e32 v10, 32, v6
	v_and_b32_e32 v6, 0xc0, v8
	v_sub_u32_e32 v0, v0, v6
	v_ashrrev_i16_sdwa v0, v230, sext(v0) dst_sel:DWORD dst_unused:UNUSED_PAD src0_sel:DWORD src1_sel:BYTE_0
	v_bfe_i32 v6, v0, 0, 16
	v_lshlrev_b32_e32 v0, 1, v9
	v_lshrrev_b32_e32 v8, 2, v9
	v_and_b32_e32 v11, 3, v5
	s_mov_b32 s0, 0x1fffe0
	v_and_b32_e32 v0, 24, v0
	v_and_b32_e32 v8, 4, v8
	v_and_or_b32 v11, v9, s0, v11
	v_or3_b32 v0, v11, v8, v0
	v_add_lshl_u32 v8, v10, v6, 1
	v_lshl_add_u32 v134, v9, 11, v8
	v_lshl_add_u32 v0, v0, 11, v8
	v_add_u32_e32 v8, 0x2000, v7
	v_ashrrev_i32_e32 v7, 31, v8
	v_lshrrev_b32_e32 v7, 22, v7
	v_add_u32_e32 v7, v8, v7
	v_ashrrev_i32_e32 v7, 10, v7
	v_mul_i32_i24_e32 v9, 0x400, v7
	v_sub_u32_e32 v8, v8, v9
	v_lshrrev_b32_e32 v9, 4, v8
	v_bitop3_b32 v9, v9, v8, 32 bitop3:0x6c
	v_lshlrev_b32_e32 v8, 3, v7
	v_and_b32_e32 v10, -16, v8
	v_ashrrev_i32_e32 v8, 31, v9
	v_lshrrev_b32_e32 v8, 26, v8
	v_add_u32_e32 v11, v9, v8
	v_ashrrev_i32_e32 v8, 6, v11
	v_add_u32_e32 v10, v8, v10
	v_and_b32_e32 v11, 0xc0, v11
	v_and_b32_e32 v14, 3, v8
	v_sub_u32_e32 v9, v9, v11
	v_and_or_b32 v14, v10, s0, v14
	s_ashr_i32 s0, s4, 6
	v_lshlrev_b32_e32 v12, 5, v7
	v_ashrrev_i16_sdwa v9, v230, sext(v9) dst_sel:DWORD dst_unused:UNUSED_PAD src0_sel:DWORD src1_sel:BYTE_0
	v_lshlrev_b32_e32 v11, 1, v10
	v_lshrrev_b32_e32 v13, 2, v10
	s_lshl_b32 s5, s0, 10
	v_and_b32_e32 v12, 32, v12
	v_bfe_i32 v9, v9, 0, 16
	v_and_b32_e32 v11, 24, v11
	v_and_b32_e32 v13, 4, v13
	s_add_i32 s6, s5, 0x10000
	v_readlane_b32 s8, v254, 58
	v_or3_b32 v11, v14, v13, v11
	v_add_lshl_u32 v12, v12, v9, 1
	s_mov_b32 m0, s6
	v_readlane_b32 s9, v254, 59
	s_add_i32 s7, s5, 0x12000
	v_lshl_add_u32 v138, v11, 11, v12
	v_readlane_b32 s12, v254, 54
	v_readlane_b32 s13, v254, 55
	v_lshl_add_u32 v136, v10, 11, v12
	global_load_lds_dwordx4 v0, s[8:9]
	s_mov_b32 m0, s7
	v_readlane_b32 s14, v254, 52
	global_load_lds_dwordx4 v138, s[8:9]
	s_mov_b32 m0, s5
	s_add_i32 s8, s5, 0x2000
	global_load_lds_dwordx4 v134, s[12:13]
	s_mov_b32 m0, s8
	s_add_i32 s9, s5, 0x14000
	global_load_lds_dwordx4 v136, s[12:13]
	s_mov_b32 m0, s9
	v_readlane_b32 s15, v254, 53
	s_add_i32 s12, s5, 0x16000
	s_add_i32 s13, s5, 0x4000
	v_readlane_b32 s18, v254, 56
	v_readlane_b32 s19, v254, 57
	s_ashr_i32 s1, s4, 8
	global_load_lds_dwordx4 v0, s[14:15]
	s_mov_b32 m0, s12
	s_nop 0
	global_load_lds_dwordx4 v138, s[14:15]
	s_mov_b32 m0, s13
	s_add_i32 s14, s5, 0x6000
	global_load_lds_dwordx4 v134, s[18:19]
	s_mov_b32 m0, s14
	s_cmp_lg_u32 s1, 1
	global_load_lds_dwordx4 v136, s[18:19]
	s_waitcnt vmcnt(8)
	v_cmp_lt_i32_e32 vcc, v224, v225
	v_lshlrev_b32_e32 v246, 16, v242
	v_and_b32_e32 v247, 0xffff0000, v242
	v_add_f32_e32 v246, v246, v247
	v_lshlrev_b32_e32 v247, 16, v243
	v_add_f32_e32 v246, v246, v247
	v_and_b32_e32 v247, 0xffff0000, v243
	v_add_f32_e32 v246, v246, v247
	v_lshlrev_b32_e32 v247, 16, v244
	v_add_f32_e32 v246, v246, v247
	v_and_b32_e32 v247, 0xffff0000, v244
	v_add_f32_e32 v246, v246, v247
	v_lshlrev_b32_e32 v247, 16, v245
	v_add_f32_e32 v246, v246, v247
	v_and_b32_e32 v247, 0xffff0000, v245
	v_add_f32_e32 v246, v246, v247
	v_cndmask_b32_e32 v247, v223, v224, vcc
	v_lshlrev_b32_e32 v151, 2, v247
	s_nop 1
	v_mov_b32_dpp v247, v246 quad_perm:[1,0,3,2] row_mask:0xf bank_mask:0xf
	s_mov_b64 exec, s[36:37]
	s_waitcnt lgkmcnt(0)
	v_add_f32_e32 v246, v246, v247
	v_fmamk_f32 v246, v246, 0x3a800000, v234
	v_mul_f32_e32 v247, 0x4b800000, v246
	v_cmp_gt_f32_e32 vcc, s97, v246
	s_nop 1
	v_cndmask_b32_e32 v246, v246, v247, vcc
	v_rsq_f32_e32 v246, v246
	s_nop 0
	v_mul_f32_e32 v247, 0x45800000, v246
	v_cndmask_b32_e32 v246, v246, v247, vcc
	ds_write_b32 v152, v246
	s_mov_b64 exec, -1
	s_cbranch_scc1 .LBB0_131
	s_barrier

; #define PG8_STAGE(bufoff, gbase, voff) do { _Pragma("unroll") for (int _i = 0; _i < 2; ++_i) \
;     __builtin_amdgcn_global_load_lds((const unsigned*)((const char*)(gbase) + (voff)[_i]), (PG8_LAS unsigned*)(lds + (bufoff) + ldsw + _i * 8192), 16, 0, 0); } while (0)
; #define PG8_WAIT_V(n) asm volatile("s_waitcnt vmcnt(" #n ")" ::: "memory")
; #define PG8_BAR __builtin_amdgcn_s_barrier()
; #define PG8_RTAB_LOAD(var, unit) do { if constexpr (Epi::NEEDS_R) { var = *(const uint4*)(E.ssq + (size_t)((unit).pm * BM + (tid >> 1)) * 16 + (tid & 1) * 8); } } while (0)
; #define PG8_RTAB_FIN(var, buf) do { if constexpr (Epi::NEEDS_R) { float ss_ = bflo(var.x) + bfhi(var.x) + bflo(var.y) + bfhi(var.y) + bflo(var.z) + bfhi(var.z) + bflo(var.w) + bfhi(var.w); ss_ += __shfl_xor(ss_, 1); \
;     if (!(tid & 1)) ((PG8_LAS float*)(lds + RT_OFF))[(buf) * 256 + (tid >> 1)] = rsqrtf(ss_ * (1.0f / DM) + EPS); } } while (0)
; template <class Epi>
; DI void gemm_phase(const bf16_t* __restrict__ gA, const bf16_t* __restrict__ gBt, int M, int N, int K, const Epi& E, char* lds_generic) {
;     ...
;   { uint4 rt0_ = {0u, 0u, 0u, 0u}; PG8_RTAB_LOAD(rt0_, cur); PG8_RTAB_FIN(rt0_, 0); }
;   bf16x8 At[4][2], B0[2][2], B1[2][2];
;   const char* cA = (const char*)gA + (size_t)cur.pm * tstep; const char* cB = (const char*)gBt + (size_t)cur.pn * tstep;
;   PG8_STAGE(PG8_SB(0, 0), cB, voffB); PG8_STAGE(PG8_SA(0, 0), cA, voffA); PG8_STAGE(PG8_SB(0, 1), cB + hstep, voffB); PG8_STAGE(PG8_SA(0, 1), cA + hstep, voffA);
;   if (wr == 1) PG8_BAR;
;   PG8_WAIT_V(4); PG8_BAR;
;   PG8_STAGE(PG8_SB(1, 0), cB + kstep, voffB); PG8_STAGE(PG8_SA(1, 0), cA + kstep, voffA); PG8_STAGE(PG8_SB(1, 1), cB + hstep + kstep, voffB);
;   PG8_WAIT_V(6); PG8_BAR;
.LBB0_147:
	s_andn2_b64 vcc, exec, s[0:1]
	s_cbranch_vccnz .LBB0_168
	v_readlane_b32 s0, v253, 37
	v_mov_b32_e32 v2, v222
	v_readlane_b32 s1, v253, 38
	s_andn2_b64 vcc, exec, s[0:1]
	v_readfirstlane_b32 s4, v2
	s_cbranch_vccnz .LBB0_168
	v_ashrrev_i32_e32 v150, 1, v2
	v_readlane_b32 s0, v254, 62
	v_and_b32_e32 v6, 1, v2
	v_lshlrev_b32_e32 v0, 4, v6
	v_add_u32_e32 v4, s0, v150
	v_ashrrev_i32_e32 v5, 31, v4
	v_lshlrev_b64 v[4:5], 5, v[4:5]
	v_lshl_add_u64 v[4:5], s[70:71], 0, v[4:5]
	v_lshl_add_u64 v[4:5], v[4:5], 0, v[0:1]
	global_load_dwordx4 v[242:245], v[4:5], off
	v_cmp_lt_i32_e32 vcc, v224, v225
	v_cmp_eq_u32_e64 s[36:37], 0, v6
	v_lshl_add_u32 v152, v150, 2, v252
	v_ashrrev_i32_e32 v0, 31, v2
	v_lshrrev_b32_e32 v0, 26, v0
	v_add_u32_e32 v0, v2, v0
	s_waitcnt lgkmcnt(0)
	v_ashrrev_i32_e32 v3, 6, v0
	v_bfe_i32 v0, v2, 27, 1
	v_lshlrev_b32_e32 v7, 4, v2
	v_lshrrev_b32_e32 v0, 22, v0
	v_add_u32_e32 v0, v7, v0
	v_and_b32_e32 v0, 0xfffffc00, v0
	v_sub_u32_e32 v0, v7, v0
	v_lshrrev_b32_e32 v4, 4, v0
	v_bitop3_b32 v0, v4, v0, 32 bitop3:0x6c
	v_lshlrev_b32_e32 v4, 3, v3
	v_and_b32_e32 v5, -16, v4
	v_ashrrev_i32_e32 v4, 31, v0
	v_lshrrev_b32_e32 v4, 26, v4
	v_add_u32_e32 v8, v0, v4
	v_ashrrev_i32_e32 v4, 6, v8
	v_add_u32_e32 v9, v4, v5
	v_lshlrev_b32_e32 v5, 5, v3
	v_and_b32_e32 v10, 32, v5
	v_and_b32_e32 v5, 0xc0, v8
	v_sub_u32_e32 v0, v0, v5
	v_ashrrev_i16_sdwa v0, v230, sext(v0) dst_sel:DWORD dst_unused:UNUSED_PAD src0_sel:DWORD src1_sel:BYTE_0
	v_bfe_i32 v5, v0, 0, 16
	v_lshlrev_b32_e32 v0, 1, v9
	v_lshrrev_b32_e32 v8, 2, v9
	v_and_b32_e32 v11, 3, v4
	s_mov_b32 s0, 0x1fffe0
	v_and_b32_e32 v0, 24, v0
	v_and_b32_e32 v8, 4, v8
	v_and_or_b32 v11, v9, s0, v11
	v_or3_b32 v0, v11, v8, v0
	v_add_lshl_u32 v8, v10, v5, 1
	v_lshl_add_u32 v134, v9, 11, v8
	v_lshl_add_u32 v0, v0, 11, v8
	v_add_u32_e32 v8, 0x2000, v7
	v_ashrrev_i32_e32 v7, 31, v8
	v_lshrrev_b32_e32 v7, 22, v7
	v_add_u32_e32 v7, v8, v7
	v_ashrrev_i32_e32 v7, 10, v7
	v_mul_i32_i24_e32 v9, 0x400, v7
	v_sub_u32_e32 v8, v8, v9
	v_lshrrev_b32_e32 v9, 4, v8
	v_bitop3_b32 v9, v9, v8, 32 bitop3:0x6c
	v_lshlrev_b32_e32 v8, 3, v7
	v_and_b32_e32 v10, -16, v8
	v_ashrrev_i32_e32 v8, 31, v9
	v_lshrrev_b32_e32 v8, 26, v8
	v_add_u32_e32 v11, v9, v8
	v_ashrrev_i32_e32 v8, 6, v11
	v_and_b32_e32 v11, 0xc0, v11
	v_add_u32_e32 v10, v8, v10
	v_sub_u32_e32 v9, v9, v11
	s_ashr_i32 s1, s4, 6
	v_lshlrev_b32_e32 v12, 5, v7
	v_ashrrev_i16_sdwa v9, v230, sext(v9) dst_sel:DWORD dst_unused:UNUSED_PAD src0_sel:DWORD src1_sel:BYTE_0
	v_lshlrev_b32_e32 v11, 1, v10
	v_lshrrev_b32_e32 v13, 2, v10
	v_and_b32_e32 v14, 3, v8
	s_lshl_b32 s5, s1, 10
	v_and_b32_e32 v12, 32, v12
	v_bfe_i32 v9, v9, 0, 16
	v_and_b32_e32 v11, 24, v11
	v_and_b32_e32 v13, 4, v13
	v_and_or_b32 v14, v10, s0, v14
	s_add_i32 s6, s5, 0x10000
	v_readlane_b32 s8, v255, 9
	v_or3_b32 v11, v14, v13, v11
	v_add_lshl_u32 v12, v12, v9, 1
	s_mov_b32 m0, s6
	v_readlane_b32 s9, v255, 10
	s_add_i32 s7, s5, 0x12000
	v_lshl_add_u32 v138, v11, 11, v12
	v_readlane_b32 s12, v255, 5
	v_readlane_b32 s13, v255, 6
	v_lshl_add_u32 v136, v10, 11, v12
	global_load_lds_dwordx4 v0, s[8:9]
	s_mov_b32 m0, s7
	v_readlane_b32 s14, v255, 3
	global_load_lds_dwordx4 v138, s[8:9]
	s_mov_b32 m0, s5
	s_add_i32 s8, s5, 0x2000
	global_load_lds_dwordx4 v134, s[12:13]
	s_mov_b32 m0, s8
	s_add_i32 s9, s5, 0x14000
	global_load_lds_dwordx4 v136, s[12:13]
	s_mov_b32 m0, s9
	v_readlane_b32 s15, v255, 4
	s_add_i32 s12, s5, 0x16000
	s_add_i32 s13, s5, 0x4000
	v_readlane_b32 s18, v255, 7
	v_readlane_b32 s19, v255, 8
	s_ashr_i32 s0, s4, 8
	global_load_lds_dwordx4 v0, s[14:15]
	s_mov_b32 m0, s12
	s_nop 0
	global_load_lds_dwordx4 v138, s[14:15]
	s_mov_b32 m0, s13
	s_add_i32 s14, s5, 0x6000
	global_load_lds_dwordx4 v134, s[18:19]
	s_mov_b32 m0, s14
	s_cmp_lg_u32 s0, 1
	global_load_lds_dwordx4 v136, s[18:19]
	s_waitcnt vmcnt(8)
	v_cmp_lt_i32_e32 vcc, v224, v225
	v_lshlrev_b32_e32 v246, 16, v242
	s_waitcnt lgkmcnt(0)
	v_and_b32_e32 v247, 0xffff0000, v242
	v_add_f32_e32 v246, v246, v247
	v_lshlrev_b32_e32 v247, 16, v243
	v_add_f32_e32 v246, v246, v247
	v_and_b32_e32 v247, 0xffff0000, v243
	v_add_f32_e32 v246, v246, v247
	v_lshlrev_b32_e32 v247, 16, v244
	v_add_f32_e32 v246, v246, v247
	v_and_b32_e32 v247, 0xffff0000, v244
	v_add_f32_e32 v246, v246, v247
	v_lshlrev_b32_e32 v247, 16, v245
	v_add_f32_e32 v246, v246, v247
	v_and_b32_e32 v247, 0xffff0000, v245
	v_add_f32_e32 v246, v246, v247
	v_cndmask_b32_e32 v247, v223, v224, vcc
	v_lshlrev_b32_e32 v151, 2, v247
	s_nop 1
	v_mov_b32_dpp v247, v246 quad_perm:[1,0,3,2] row_mask:0xf bank_mask:0xf
	s_mov_b64 exec, s[36:37]
	s_waitcnt lgkmcnt(0)
	v_add_f32_e32 v246, v246, v247
	v_fmamk_f32 v246, v246, 0x3a800000, v234
	v_mul_f32_e32 v247, 0x4b800000, v246
	v_cmp_gt_f32_e32 vcc, s97, v246
	s_nop 1
	v_cndmask_b32_e32 v246, v246, v247, vcc
	v_rsq_f32_e32 v246, v246
	s_nop 0
	v_mul_f32_e32 v247, 0x45800000, v246
	v_cndmask_b32_e32 v246, v246, v247, vcc
	ds_write_b32 v152, v246
	s_mov_b64 exec, -1
	s_cbranch_scc1 .LBB0_153
	s_barrier

; #define PG8_STAGE(bufoff, gbase, voff) do { _Pragma("unroll") for (int _i = 0; _i < 2; ++_i) \
;     __builtin_amdgcn_global_load_lds((const unsigned*)((const char*)(gbase) + (voff)[_i]), (PG8_LAS unsigned*)(lds + (bufoff) + ldsw + _i * 8192), 16, 0, 0); } while (0)
; #define PG8_WAIT_V(n) asm volatile("s_waitcnt vmcnt(" #n ")" ::: "memory")
; #define PG8_BAR __builtin_amdgcn_s_barrier()
; #define PG8_RTAB_LOAD(var, unit) do { if constexpr (Epi::NEEDS_R) { var = *(const uint4*)(E.ssq + (size_t)((unit).pm * BM + (tid >> 1)) * 16 + (tid & 1) * 8); } } while (0)
; #define PG8_RTAB_FIN(var, buf) do { if constexpr (Epi::NEEDS_R) { float ss_ = bflo(var.x) + bfhi(var.x) + bflo(var.y) + bfhi(var.y) + bflo(var.z) + bfhi(var.z) + bflo(var.w) + bfhi(var.w); ss_ += __shfl_xor(ss_, 1); \
;     if (!(tid & 1)) ((PG8_LAS float*)(lds + RT_OFF))[(buf) * 256 + (tid >> 1)] = rsqrtf(ss_ * (1.0f / DM) + EPS); } } while (0)
; template <class Epi>
; DI void gemm_phase(const bf16_t* __restrict__ gA, const bf16_t* __restrict__ gBt, int M, int N, int K, const Epi& E, char* lds_generic) {
;     ...
;   { uint4 rt0_ = {0u, 0u, 0u, 0u}; PG8_RTAB_LOAD(rt0_, cur); PG8_RTAB_FIN(rt0_, 0); }
;   bf16x8 At[4][2], B0[2][2], B1[2][2];
;   const char* cA = (const char*)gA + (size_t)cur.pm * tstep; const char* cB = (const char*)gBt + (size_t)cur.pn * tstep;
;   PG8_STAGE(PG8_SB(0, 0), cB, voffB); PG8_STAGE(PG8_SA(0, 0), cA, voffA); PG8_STAGE(PG8_SB(0, 1), cB + hstep, voffB); PG8_STAGE(PG8_SA(0, 1), cA + hstep, voffA);
;   if (wr == 1) PG8_BAR;
;   PG8_WAIT_V(4); PG8_BAR;
;   PG8_STAGE(PG8_SB(1, 0), cB + kstep, voffB); PG8_STAGE(PG8_SA(1, 0), cA + kstep, voffA); PG8_STAGE(PG8_SB(1, 1), cB + hstep + kstep, voffB);
;   PG8_WAIT_V(6); PG8_BAR;
.LBB0_590:
	v_readlane_b32 s0, v255, 19
	s_mul_hi_u32 s1, s33, s0
	s_mul_i32 s0, s33, s0
	s_lshl_b64 s[6:7], s[0:1], 11
	s_add_u32 s82, s92, s6
	s_addc_u32 s83, s93, s7
	s_lshl_b64 s[6:7], s[0:1], 5
	s_add_u32 s84, s70, s6
	s_addc_u32 s85, s71, s7
	v_readlane_b32 s6, v255, 13
	v_mov_b32_e32 v2, v222
	v_readlane_b32 s7, v255, 14
	s_andn2_b64 vcc, exec, s[6:7]
	v_readfirstlane_b32 s76, v2
	s_cbranch_vccnz .LBB0_614
	v_ashrrev_i32_e32 v150, 1, v2
	v_readlane_b32 s6, v255, 26
	v_cmp_lt_i32_e32 vcc, v224, v225
	v_lshl_add_u32 v152, v150, 2, v252
	v_add_u32_e32 v4, s6, v150
	v_ashrrev_i32_e32 v5, 31, v4
	v_lshlrev_b64 v[4:5], 5, v[4:5]
	v_lshl_add_u64 v[6:7], s[84:85], 0, v[4:5]
	v_and_b32_e32 v4, 1, v2
	v_lshlrev_b32_e32 v0, 4, v4
	v_lshl_add_u64 v[6:7], v[6:7], 0, v[0:1]
	global_load_dwordx4 v[242:245], v[6:7], off
	v_cmp_eq_u32_e64 s[36:37], 0, v4
	v_ashrrev_i32_e32 v0, 31, v2
	v_lshrrev_b32_e32 v0, 26, v0
	v_add_u32_e32 v0, v2, v0
	s_waitcnt lgkmcnt(0)
	v_ashrrev_i32_e32 v3, 6, v0
	v_bfe_i32 v0, v2, 27, 1
	v_lshlrev_b32_e32 v7, 4, v2
	v_lshrrev_b32_e32 v0, 22, v0
	v_add_u32_e32 v0, v7, v0
	v_and_b32_e32 v0, 0xfffffc00, v0
	v_sub_u32_e32 v0, v7, v0
	v_lshrrev_b32_e32 v5, 4, v0
	v_bitop3_b32 v0, v5, v0, 32 bitop3:0x6c
	v_lshlrev_b32_e32 v5, 3, v3
	v_and_b32_e32 v6, -16, v5
	v_ashrrev_i32_e32 v5, 31, v0
	v_lshrrev_b32_e32 v5, 26, v5
	v_add_u32_e32 v8, v0, v5
	v_ashrrev_i32_e32 v5, 6, v8
	v_add_u32_e32 v9, v5, v6
	v_lshlrev_b32_e32 v6, 5, v3
	v_and_b32_e32 v10, 32, v6
	v_and_b32_e32 v6, 0xc0, v8
	v_sub_u32_e32 v0, v0, v6
	v_ashrrev_i16_sdwa v0, v230, sext(v0) dst_sel:DWORD dst_unused:UNUSED_PAD src0_sel:DWORD src1_sel:BYTE_0
	v_bfe_i32 v6, v0, 0, 16
	v_lshlrev_b32_e32 v0, 1, v9
	v_lshrrev_b32_e32 v8, 2, v9
	v_and_b32_e32 v11, 3, v5
	s_mov_b32 s6, 0x1fffe0
	v_and_b32_e32 v0, 24, v0
	v_and_b32_e32 v8, 4, v8
	v_and_or_b32 v11, v9, s6, v11
	v_or3_b32 v0, v11, v8, v0
	v_add_lshl_u32 v8, v10, v6, 1
	v_lshl_add_u32 v134, v9, 11, v8
	v_lshl_add_u32 v0, v0, 11, v8
	v_add_u32_e32 v8, 0x2000, v7
	v_ashrrev_i32_e32 v7, 31, v8
	v_lshrrev_b32_e32 v7, 22, v7
	v_add_u32_e32 v7, v8, v7
	v_ashrrev_i32_e32 v7, 10, v7
	v_mul_i32_i24_e32 v9, 0x400, v7
	v_sub_u32_e32 v8, v8, v9
	v_lshrrev_b32_e32 v9, 4, v8
	v_bitop3_b32 v9, v9, v8, 32 bitop3:0x6c
	v_lshlrev_b32_e32 v8, 3, v7
	v_and_b32_e32 v10, -16, v8
	v_ashrrev_i32_e32 v8, 31, v9
	v_lshrrev_b32_e32 v8, 26, v8
	v_add_u32_e32 v11, v9, v8
	v_ashrrev_i32_e32 v8, 6, v11
	v_add_u32_e32 v10, v8, v10
	v_and_b32_e32 v11, 0xc0, v11
	v_and_b32_e32 v14, 3, v8
	v_sub_u32_e32 v9, v9, v11
	v_and_or_b32 v14, v10, s6, v14
	s_ashr_i32 s6, s76, 6
	v_lshlrev_b32_e32 v12, 5, v7
	v_ashrrev_i16_sdwa v9, v230, sext(v9) dst_sel:DWORD dst_unused:UNUSED_PAD src0_sel:DWORD src1_sel:BYTE_0
	v_lshlrev_b32_e32 v11, 1, v10
	v_lshrrev_b32_e32 v13, 2, v10
	s_lshl_b32 s72, s6, 10
	v_and_b32_e32 v12, 32, v12
	v_bfe_i32 v9, v9, 0, 16
	v_and_b32_e32 v11, 24, v11
	v_and_b32_e32 v13, 4, v13
	s_add_i32 s14, s72, 0x10000
	s_ashr_i32 s8, s76, 8
	v_or3_b32 v11, v14, v13, v11
	v_add_lshl_u32 v12, v12, v9, 1
	s_mov_b32 m0, s14
	s_add_i32 s15, s72, 0x12000
	v_readlane_b32 s12, v255, 29
	v_lshl_add_u32 v138, v11, 11, v12
	global_load_lds_dwordx4 v0, s[40:41]
	s_mov_b32 m0, s15
	v_readlane_b32 s13, v255, 30
	s_add_u32 s28, s82, s12
	global_load_lds_dwordx4 v138, s[40:41]
	s_addc_u32 s29, s83, s13
	s_mov_b32 m0, s72
	s_add_i32 s58, s72, 0x2000
	v_lshl_add_u32 v136, v10, 11, v12
	global_load_lds_dwordx4 v134, s[28:29]
	s_mov_b32 m0, s58
	s_add_i32 s59, s72, 0x14000
	s_add_i32 s62, s72, 0x16000
	global_load_lds_dwordx4 v136, s[28:29]
	s_mov_b32 m0, s59
	s_add_u32 s18, s28, 0x40000
	global_load_lds_dwordx4 v0, s[78:79]
	s_mov_b32 m0, s62
	s_addc_u32 s19, s29, 0
	s_add_i32 s7, s72, 0x4000
	global_load_lds_dwordx4 v138, s[78:79]
	s_mov_b32 m0, s7
	s_add_i32 s12, s72, 0x6000
	global_load_lds_dwordx4 v134, s[18:19]
	s_mov_b32 m0, s12
	s_cmp_lg_u32 s8, 1
	global_load_lds_dwordx4 v136, s[18:19]
	s_waitcnt vmcnt(8)
	v_cmp_lt_i32_e32 vcc, v224, v225
	v_lshlrev_b32_e32 v246, 16, v242
	v_and_b32_e32 v247, 0xffff0000, v242
	v_add_f32_e32 v246, v246, v247
	v_lshlrev_b32_e32 v247, 16, v243
	v_add_f32_e32 v246, v246, v247
	v_and_b32_e32 v247, 0xffff0000, v243
	v_add_f32_e32 v246, v246, v247
	v_lshlrev_b32_e32 v247, 16, v244
	v_add_f32_e32 v246, v246, v247
	v_and_b32_e32 v247, 0xffff0000, v244
	v_add_f32_e32 v246, v246, v247
	v_lshlrev_b32_e32 v247, 16, v245
	v_add_f32_e32 v246, v246, v247
	v_and_b32_e32 v247, 0xffff0000, v245
	v_add_f32_e32 v246, v246, v247
	v_cndmask_b32_e32 v247, v223, v224, vcc
	v_lshlrev_b32_e32 v151, 2, v247
	s_nop 1
	v_mov_b32_dpp v247, v246 quad_perm:[1,0,3,2] row_mask:0xf bank_mask:0xf
	s_and_saveexec_b64 s[26:27], s[36:37]
	s_cbranch_execz .LBB0_593
	s_waitcnt lgkmcnt(0)
	v_add_f32_e32 v246, v246, v247
	v_fmamk_f32 v246, v246, 0x3a800000, v234
	v_mul_f32_e32 v247, 0x4b800000, v246
	v_cmp_gt_f32_e32 vcc, s97, v246
	s_nop 1
	v_cndmask_b32_e32 v246, v246, v247, vcc
	v_rsq_f32_e32 v246, v246
	s_nop 0
	v_mul_f32_e32 v247, 0x45800000, v246
	v_cndmask_b32_e32 v246, v246, v247, vcc
	ds_write_b32 v152, v246
.LBB0_593:
	s_or_b64 exec, exec, s[26:27]
	s_cmp_lg_u32 s8, 1
	s_cbranch_scc1 .LBB0_595
	s_barrier
